# v2 plus residual-add GEMM epilogue (out-proj, down) rewritten by hand: 16 residual loads batched, batched cross-lane reduce, global instead of flat ops
# baseline (speedup 1.0000x reference)
; #define PG8_STAGE(bufoff, gbase, voff) do { _Pragma("unroll") for (int _i = 0; _i < 2; ++_i) \
;         __builtin_amdgcn_global_load_lds((const unsigned*)((const char*)(gbase) + (voff)[_i]), (PG8_LAS unsigned*)(lds + (bufoff) + ldsw + _i * 8192), 16, 0, 0); } while (0)
; #define PG8_LDA(dst, b, h) do { _Pragma("unroll") for (int m = 0; m < 4; ++m) _Pragma("unroll") for (int k = 0; k < 2; ++k) dst[m][k] = *(const PG8_LAS bf16x8*)(lds + PG8_SA(b, h) + aoff + m * 2048 + k * 1024); } while (0)
; #define PG8_LDB(dst, b, h) do { _Pragma("unroll") for (int n = 0; n < 2; ++n) _Pragma("unroll") for (int k = 0; k < 2; ++k) dst[n][k] = *(const PG8_LAS bf16x8*)(lds + PG8_SB(b, h) + boff + n * 2048 + k * 1024); } while (0)
; #define PG8_MMA(ai, bj, At, Bt) do { __builtin_amdgcn_s_setprio(1); _Pragma("unroll") for (int m = 0; m < 4; ++m) _Pragma("unroll") for (int n = 0; n < 2; ++n) _Pragma("unroll") for (int k = 0; k < 2; ++k) \
;         acc[ai][bj][m][n] = __builtin_amdgcn_mfma_f32_16x16x32_bf16(Bt[n][k], At[m][k], acc[ai][bj][m][n], 0, 0, 0); __builtin_amdgcn_s_setprio(0); } while (0)
; template <class Epi, class Sched, bool ALIGN_EPI = false, bool SP2 = false>
; __device__ __forceinline__ void gemm_phase(PG8_LAS unsigned char* lds, const Gemm g, const Sched& S, const Epi& E, const int wave_in) {
;     ...
;         const bool has_next = S.next(ui + 1, nxt);
;         const char* nA = has_next ? (const char*)g.A + (size_t)nxt.pm * tstep : cA; const char* nB = has_next ? (const char*)g.Bt + (size_t)nxt.pn * tstep : cB;
;         for (int t = 0; t < nt; t += 2) {
;             const bool last = (t == nt - 2);
;             const char* a1 = cA + (size_t)(t + 1) * kstep;
;             const char* a2 = last ? nA : cA + (size_t)(t + 2) * kstep; const char* b2 = last ? nB : cB + (size_t)(t + 2) * kstep;
;             const char* a3 = a2 + kstep; const char* b3 = b2 + kstep;
;             if (last && has_next) S.a_ready(nxt);
;             if constexpr (SP2) {
;             PG8_LDB(B0, 0, 0); PG8_LDB(B1, 0, 1); PG8_SCHED; PG8_LDA(At, 0, 0); PG8_STAGE(PG8_SA(1, 1), a1 + hstep, voffA);
;             PG8_WAIT_V(8); PG8_WAIT_L(0); PG8_BAR; PG8_MMA(0, 0, At, B0); PG8_MMA(0, 1, At, B1); PG8_BAR; PG8_SCHED;
;             PG8_LDA(At, 0, 1); PG8_STAGE(PG8_SB(0, 0), b2, voffB); PG8_STAGE(PG8_SB(0, 1), b2 + hstep, voffB); PG8_STAGE(PG8_SA(0, 0), a2, voffA);
.LBB0_59:
	s_add_i32 s72, s24, 2
	s_add_u32 s73, s20, 0x80
	s_addc_u32 s25, s21, 0
	s_add_i32 s76, 0, 0x10000
	s_cmp_eq_u32 s68, s24
	s_cselect_b32 s25, s1, s25
	s_cselect_b32 s24, s0, s73
	s_cselect_b32 s75, s19, s45
	s_cselect_b32 s74, s18, s44
	s_add_i32 s73, 0, 0x14000
	v_add_u32_e32 v140, s76, v191
	v_add_u32_e32 v166, s73, v191
	ds_read_b128 v[120:123], v140
	ds_read_b128 v[132:135], v140 offset:1024
	ds_read_b128 v[136:139], v140 offset:2048
	ds_read_b128 v[140:143], v140 offset:3072
	ds_read_b128 v[144:147], v166
	ds_read_b128 v[148:151], v166 offset:1024
	ds_read_b128 v[152:155], v166 offset:2048
	ds_read_b128 v[166:169], v166 offset:3072
	v_lshl_add_u64 v[206:207], s[20:21], 0, v[164:165]
	s_add_i32 m0, s30, 0xc000
	ds_read_b128 v[170:173], v193
	ds_read_b128 v[174:177], v193 offset:1024
	ds_read_b128 v[178:181], v193 offset:2048
	ds_read_b128 v[182:185], v193 offset:3072
	ds_read_b128 v[186:189], v193 offset:4096
	ds_read_b128 v[194:197], v193 offset:5120
	ds_read_b128 v[198:201], v193 offset:6144
	ds_read_b128 v[202:205], v193 offset:7168
	global_load_lds_dwordx4 v[206:207], off
	v_lshl_add_u64 v[206:207], s[20:21], 0, v[162:163]
	s_add_i32 m0, s30, 0xe000
	s_nop 0
	global_load_lds_dwordx4 v[206:207], off
	s_waitcnt vmcnt(8)
	s_waitcnt lgkmcnt(0)
	s_barrier
	s_setprio 1
	s_waitcnt lgkmcnt(0)
	v_mfma_f32_16x16x32_bf16 v[128:131], v[120:123], v[170:173], v[128:131]
	v_mfma_f32_16x16x32_bf16 v[124:127], v[136:139], v[170:173], v[124:127]
	v_mfma_f32_16x16x32_bf16 v[108:111], v[120:123], v[178:181], v[108:111]
	v_mfma_f32_16x16x32_bf16 v[104:107], v[136:139], v[178:181], v[104:107]
	v_mfma_f32_16x16x32_bf16 v[92:95], v[120:123], v[186:189], v[92:95]
	v_mfma_f32_16x16x32_bf16 v[88:91], v[136:139], v[186:189], v[88:91]
	v_mfma_f32_16x16x32_bf16 v[76:79], v[120:123], v[198:201], v[76:79]
	v_mfma_f32_16x16x32_bf16 v[72:75], v[136:139], v[198:201], v[72:75]
	v_mfma_f32_16x16x32_bf16 v[128:131], v[132:135], v[174:177], v[128:131]
	v_mfma_f32_16x16x32_bf16 v[124:127], v[140:143], v[174:177], v[124:127]
	v_mfma_f32_16x16x32_bf16 v[108:111], v[132:135], v[182:185], v[108:111]
	v_mfma_f32_16x16x32_bf16 v[104:107], v[140:143], v[182:185], v[104:107]
	v_mfma_f32_16x16x32_bf16 v[92:95], v[132:135], v[194:197], v[92:95]
	v_mfma_f32_16x16x32_bf16 v[88:91], v[140:143], v[194:197], v[88:91]
	v_mfma_f32_16x16x32_bf16 v[76:79], v[132:135], v[202:205], v[76:79]
	v_mfma_f32_16x16x32_bf16 v[72:75], v[140:143], v[202:205], v[72:75]
	s_setprio 0
	s_setprio 1
	v_mfma_f32_16x16x32_bf16 v[116:119], v[144:147], v[170:173], v[116:119]
	v_mfma_f32_16x16x32_bf16 v[112:115], v[152:155], v[170:173], v[112:115]
	v_mfma_f32_16x16x32_bf16 v[100:103], v[144:147], v[178:181], v[100:103]
	v_mfma_f32_16x16x32_bf16 v[96:99], v[152:155], v[178:181], v[96:99]
	v_mfma_f32_16x16x32_bf16 v[84:87], v[144:147], v[186:189], v[84:87]
	v_mfma_f32_16x16x32_bf16 v[80:83], v[152:155], v[186:189], v[80:83]
	v_mfma_f32_16x16x32_bf16 v[68:71], v[144:147], v[198:201], v[68:71]
	v_mfma_f32_16x16x32_bf16 v[64:67], v[152:155], v[198:201], v[64:67]
	v_mfma_f32_16x16x32_bf16 v[116:119], v[148:151], v[174:177], v[116:119]
	v_mfma_f32_16x16x32_bf16 v[112:115], v[166:169], v[174:177], v[112:115]
	v_mfma_f32_16x16x32_bf16 v[100:103], v[148:151], v[182:185], v[100:103]
	v_mfma_f32_16x16x32_bf16 v[96:99], v[166:169], v[182:185], v[96:99]
	v_mfma_f32_16x16x32_bf16 v[84:87], v[148:151], v[194:197], v[84:87]
	v_mfma_f32_16x16x32_bf16 v[80:83], v[166:169], v[194:197], v[80:83]
	v_mfma_f32_16x16x32_bf16 v[68:71], v[148:151], v[202:205], v[68:71]
	v_mfma_f32_16x16x32_bf16 v[64:67], v[166:169], v[202:205], v[64:67]
	s_setprio 0
	s_barrier
	s_add_i32 s76, s76, s29
	v_lshl_add_u64 v[206:207], s[74:75], 0, v[208:209]
	s_mov_b32 m0, s76
	ds_read_b128 v[170:173], v193 offset:16384
	ds_read_b128 v[174:177], v193 offset:17408
	ds_read_b128 v[178:181], v193 offset:18432
	ds_read_b128 v[182:185], v193 offset:19456
	ds_read_b128 v[186:189], v193 offset:20480
	ds_read_b128 v[194:197], v193 offset:21504
	ds_read_b128 v[198:201], v193 offset:22528
	ds_read_b128 v[202:205], v193 offset:23552
	global_load_lds_dwordx4 v[206:207], off
	s_add_i32 m0, s76, 0x2000
	v_lshl_add_u64 v[214:215], s[74:75], 0, v[156:157]
	s_add_u32 s74, s74, s4
	s_addc_u32 s75, s75, 0
	s_add_i32 s73, s73, s29
	global_load_lds_dwordx4 v[214:215], off
	v_lshl_add_u64 v[216:217], s[74:75], 0, v[208:209]
	s_mov_b32 m0, s73
	v_lshl_add_u64 v[232:233], s[74:75], 0, v[156:157]
	global_load_lds_dwordx4 v[216:217], off
	s_add_i32 m0, s73, 0x2000
	v_lshl_add_u64 v[234:235], s[24:25], 0, v[160:161]
	global_load_lds_dwordx4 v[232:233], off
	s_mov_b32 m0, s30
	v_lshl_add_u64 v[236:237], s[24:25], 0, v[158:159]
	global_load_lds_dwordx4 v[234:235], off
	s_mov_b32 m0, s31
	s_nop 0
	global_load_lds_dwordx4 v[236:237], off
	s_waitcnt vmcnt(8)
	s_waitcnt lgkmcnt(0)
	s_barrier
; #define PG8_STAGE(bufoff, gbase, voff) do { _Pragma("unroll") for (int _i = 0; _i < 2; ++_i) \
;         __builtin_amdgcn_global_load_lds((const unsigned*)((const char*)(gbase) + (voff)[_i]), (PG8_LAS unsigned*)(lds + (bufoff) + ldsw + _i * 8192), 16, 0, 0); } while (0)
; #define PG8_LDA(dst, b, h) do { _Pragma("unroll") for (int m = 0; m < 4; ++m) _Pragma("unroll") for (int k = 0; k < 2; ++k) dst[m][k] = *(const PG8_LAS bf16x8*)(lds + PG8_SA(b, h) + aoff + m * 2048 + k * 1024); } while (0)
; #define PG8_LDB(dst, b, h) do { _Pragma("unroll") for (int n = 0; n < 2; ++n) _Pragma("unroll") for (int k = 0; k < 2; ++k) dst[n][k] = *(const PG8_LAS bf16x8*)(lds + PG8_SB(b, h) + boff + n * 2048 + k * 1024); } while (0)
; #define PG8_MMA(ai, bj, At, Bt) do { __builtin_amdgcn_s_setprio(1); _Pragma("unroll") for (int m = 0; m < 4; ++m) _Pragma("unroll") for (int n = 0; n < 2; ++n) _Pragma("unroll") for (int k = 0; k < 2; ++k) \
;         acc[ai][bj][m][n] = __builtin_amdgcn_mfma_f32_16x16x32_bf16(Bt[n][k], At[m][k], acc[ai][bj][m][n], 0, 0, 0); __builtin_amdgcn_s_setprio(0); } while (0)
; #define PG8_WAIT_V(n) asm volatile("s_waitcnt vmcnt(" #n ")" ::: "memory")
; #define PG8_WAIT_L(n) asm volatile("s_waitcnt lgkmcnt(" #n ")" ::: "memory")
; #define PG8_BAR __builtin_amdgcn_s_barrier()
; #define PG8_SCHED __builtin_amdgcn_sched_barrier(0)
; template <class Epi, class Sched, bool ALIGN_EPI = false, bool SP2 = false>
; __device__ __forceinline__ void gemm_phase(PG8_LAS unsigned char* lds, const Gemm g, const Sched& S, const Epi& E, const int wave_in) {
;     ...
;             PG8_WAIT_V(8); PG8_WAIT_L(0); PG8_BAR; PG8_MMA(1, 0, At, B0); PG8_MMA(1, 1, At, B1); PG8_BAR; PG8_SCHED;
;             PG8_LDB(B0, 1, 0); PG8_LDB(B1, 1, 1); PG8_SCHED; PG8_LDA(At, 1, 0); PG8_STAGE(PG8_SA(0, 1), a2 + hstep, voffA);
;             PG8_WAIT_V(8); PG8_WAIT_L(0); PG8_BAR; PG8_MMA(0, 0, At, B0); PG8_MMA(0, 1, At, B1); PG8_BAR; PG8_SCHED;
	s_setprio 1
	s_waitcnt lgkmcnt(0)
	v_mfma_f32_16x16x32_bf16 v[60:63], v[120:123], v[170:173], v[60:63]
	v_mfma_f32_16x16x32_bf16 v[56:59], v[136:139], v[170:173], v[56:59]
	v_mfma_f32_16x16x32_bf16 v[44:47], v[120:123], v[178:181], v[44:47]
	v_mfma_f32_16x16x32_bf16 v[40:43], v[136:139], v[178:181], v[40:43]
	v_mfma_f32_16x16x32_bf16 v[28:31], v[120:123], v[186:189], v[28:31]
	v_mfma_f32_16x16x32_bf16 v[24:27], v[136:139], v[186:189], v[24:27]
	v_mfma_f32_16x16x32_bf16 v[12:15], v[120:123], v[198:201], v[12:15]
	v_mfma_f32_16x16x32_bf16 v[8:11], v[136:139], v[198:201], v[8:11]
	v_mfma_f32_16x16x32_bf16 v[60:63], v[132:135], v[174:177], v[60:63]
	v_mfma_f32_16x16x32_bf16 v[56:59], v[140:143], v[174:177], v[56:59]
	v_mfma_f32_16x16x32_bf16 v[44:47], v[132:135], v[182:185], v[44:47]
	v_mfma_f32_16x16x32_bf16 v[40:43], v[140:143], v[182:185], v[40:43]
	v_mfma_f32_16x16x32_bf16 v[28:31], v[132:135], v[194:197], v[28:31]
	v_mfma_f32_16x16x32_bf16 v[24:27], v[140:143], v[194:197], v[24:27]
	v_mfma_f32_16x16x32_bf16 v[12:15], v[132:135], v[202:205], v[12:15]
	v_mfma_f32_16x16x32_bf16 v[8:11], v[140:143], v[202:205], v[8:11]
	s_setprio 0
	s_setprio 1
	v_mfma_f32_16x16x32_bf16 v[52:55], v[144:147], v[170:173], v[52:55]
	v_mfma_f32_16x16x32_bf16 v[48:51], v[152:155], v[170:173], v[48:51]
	v_mfma_f32_16x16x32_bf16 v[36:39], v[144:147], v[178:181], v[36:39]
	v_mfma_f32_16x16x32_bf16 v[32:35], v[152:155], v[178:181], v[32:35]
	v_mfma_f32_16x16x32_bf16 v[20:23], v[144:147], v[186:189], v[20:23]
	v_mfma_f32_16x16x32_bf16 v[16:19], v[152:155], v[186:189], v[16:19]
	v_mfma_f32_16x16x32_bf16 v[4:7], v[144:147], v[198:201], v[4:7]
	v_mfma_f32_16x16x32_bf16 v[0:3], v[152:155], v[198:201], v[0:3]
	v_mfma_f32_16x16x32_bf16 v[52:55], v[148:151], v[174:177], v[52:55]
	v_mfma_f32_16x16x32_bf16 v[48:51], v[166:169], v[174:177], v[48:51]
	v_mfma_f32_16x16x32_bf16 v[36:39], v[148:151], v[182:185], v[36:39]
	v_mfma_f32_16x16x32_bf16 v[32:35], v[166:169], v[182:185], v[32:35]
	v_mfma_f32_16x16x32_bf16 v[20:23], v[148:151], v[194:197], v[20:23]
	v_mfma_f32_16x16x32_bf16 v[16:19], v[166:169], v[194:197], v[16:19]
	v_mfma_f32_16x16x32_bf16 v[4:7], v[148:151], v[202:205], v[4:7]
	v_mfma_f32_16x16x32_bf16 v[0:3], v[166:169], v[202:205], v[0:3]
	s_setprio 0
	s_barrier
	s_add_i32 s73, 0, 0x18000
	s_add_i32 s74, 0, 0x1c000
	v_add_u32_e32 v140, s73, v191
	v_add_u32_e32 v166, s74, v191
	ds_read_b128 v[120:123], v140
	ds_read_b128 v[132:135], v140 offset:1024
	ds_read_b128 v[136:139], v140 offset:2048
	ds_read_b128 v[140:143], v140 offset:3072
	ds_read_b128 v[144:147], v166
	ds_read_b128 v[148:151], v166 offset:1024
	ds_read_b128 v[152:155], v166 offset:2048
	ds_read_b128 v[166:169], v166 offset:3072
	s_add_u32 s24, s24, s4
	s_addc_u32 s25, s25, 0
	s_mov_b32 m0, s33
	v_lshl_add_u64 v[238:239], s[24:25], 0, v[160:161]
	ds_read_b128 v[170:173], v193 offset:32768
	ds_read_b128 v[174:177], v193 offset:33792
	ds_read_b128 v[178:181], v193 offset:34816
	ds_read_b128 v[182:185], v193 offset:35840
	ds_read_b128 v[186:189], v193 offset:36864
	ds_read_b128 v[194:197], v193 offset:37888
	ds_read_b128 v[198:201], v193 offset:38912
	ds_read_b128 v[202:205], v193 offset:39936
	global_load_lds_dwordx4 v[238:239], off
	v_lshl_add_u64 v[238:239], s[24:25], 0, v[158:159]
	s_mov_b32 m0, s36
	s_nop 0
	global_load_lds_dwordx4 v[238:239], off
	s_waitcnt vmcnt(8)
	s_waitcnt lgkmcnt(0)
	s_barrier
	s_setprio 1
	s_waitcnt lgkmcnt(0)
	v_mfma_f32_16x16x32_bf16 v[128:131], v[120:123], v[170:173], v[128:131]
	v_mfma_f32_16x16x32_bf16 v[124:127], v[136:139], v[170:173], v[124:127]
	v_mfma_f32_16x16x32_bf16 v[108:111], v[120:123], v[178:181], v[108:111]
	v_mfma_f32_16x16x32_bf16 v[104:107], v[136:139], v[178:181], v[104:107]
	v_mfma_f32_16x16x32_bf16 v[92:95], v[120:123], v[186:189], v[92:95]
	v_mfma_f32_16x16x32_bf16 v[88:91], v[136:139], v[186:189], v[88:91]
	v_mfma_f32_16x16x32_bf16 v[76:79], v[120:123], v[198:201], v[76:79]
	v_mfma_f32_16x16x32_bf16 v[72:75], v[136:139], v[198:201], v[72:75]
	v_mfma_f32_16x16x32_bf16 v[128:131], v[132:135], v[174:177], v[128:131]
	v_mfma_f32_16x16x32_bf16 v[124:127], v[140:143], v[174:177], v[124:127]
	v_mfma_f32_16x16x32_bf16 v[108:111], v[132:135], v[182:185], v[108:111]
	v_mfma_f32_16x16x32_bf16 v[104:107], v[140:143], v[182:185], v[104:107]
	v_mfma_f32_16x16x32_bf16 v[92:95], v[132:135], v[194:197], v[92:95]
	v_mfma_f32_16x16x32_bf16 v[88:91], v[140:143], v[194:197], v[88:91]
	v_mfma_f32_16x16x32_bf16 v[76:79], v[132:135], v[202:205], v[76:79]
	v_mfma_f32_16x16x32_bf16 v[72:75], v[140:143], v[202:205], v[72:75]
	s_setprio 0
	s_setprio 1
	v_mfma_f32_16x16x32_bf16 v[116:119], v[144:147], v[170:173], v[116:119]
	v_mfma_f32_16x16x32_bf16 v[112:115], v[152:155], v[170:173], v[112:115]
	v_mfma_f32_16x16x32_bf16 v[100:103], v[144:147], v[178:181], v[100:103]
	v_mfma_f32_16x16x32_bf16 v[96:99], v[152:155], v[178:181], v[96:99]
	v_mfma_f32_16x16x32_bf16 v[84:87], v[144:147], v[186:189], v[84:87]
	v_mfma_f32_16x16x32_bf16 v[80:83], v[152:155], v[186:189], v[80:83]
	v_mfma_f32_16x16x32_bf16 v[68:71], v[144:147], v[198:201], v[68:71]
	v_mfma_f32_16x16x32_bf16 v[64:67], v[152:155], v[198:201], v[64:67]
	v_mfma_f32_16x16x32_bf16 v[116:119], v[148:151], v[174:177], v[116:119]
	v_mfma_f32_16x16x32_bf16 v[112:115], v[166:169], v[174:177], v[112:115]
	v_mfma_f32_16x16x32_bf16 v[100:103], v[148:151], v[182:185], v[100:103]
	v_mfma_f32_16x16x32_bf16 v[96:99], v[166:169], v[182:185], v[96:99]
	v_mfma_f32_16x16x32_bf16 v[84:87], v[148:151], v[194:197], v[84:87]
	v_mfma_f32_16x16x32_bf16 v[80:83], v[166:169], v[194:197], v[80:83]
	v_mfma_f32_16x16x32_bf16 v[68:71], v[148:151], v[202:205], v[68:71]
	v_mfma_f32_16x16x32_bf16 v[64:67], v[166:169], v[202:205], v[64:67]
	s_setprio 0
	s_barrier
; #define PG8_STAGE(bufoff, gbase, voff) do { _Pragma("unroll") for (int _i = 0; _i < 2; ++_i) \
;         __builtin_amdgcn_global_load_lds((const unsigned*)((const char*)(gbase) + (voff)[_i]), (PG8_LAS unsigned*)(lds + (bufoff) + ldsw + _i * 8192), 16, 0, 0); } while (0)
; #define PG8_LDA(dst, b, h) do { _Pragma("unroll") for (int m = 0; m < 4; ++m) _Pragma("unroll") for (int k = 0; k < 2; ++k) dst[m][k] = *(const PG8_LAS bf16x8*)(lds + PG8_SA(b, h) + aoff + m * 2048 + k * 1024); } while (0)
; #define PG8_MMA(ai, bj, At, Bt) do { __builtin_amdgcn_s_setprio(1); _Pragma("unroll") for (int m = 0; m < 4; ++m) _Pragma("unroll") for (int n = 0; n < 2; ++n) _Pragma("unroll") for (int k = 0; k < 2; ++k) \
;         acc[ai][bj][m][n] = __builtin_amdgcn_mfma_f32_16x16x32_bf16(Bt[n][k], At[m][k], acc[ai][bj][m][n], 0, 0, 0); __builtin_amdgcn_s_setprio(0); } while (0)
; #define PG8_WAIT_V(n) asm volatile("s_waitcnt vmcnt(" #n ")" ::: "memory")
; #define PG8_WAIT_L(n) asm volatile("s_waitcnt lgkmcnt(" #n ")" ::: "memory")
; #define PG8_BAR __builtin_amdgcn_s_barrier()
; #define PG8_SCHED __builtin_amdgcn_sched_barrier(0)
;     __device__ __forceinline__ void operator()(const f32x4 (&acc)[2][2][4][2], const Unit& u, int wr, int wc, int fr, int fq) const {
;     ...
;             for (int m = 0; m < 4; ++m)
; #pragma unroll
;                 for (int bj = 0; bj < 2; ++bj) res[m][bj] = *(const u32x4*)(xb + (size_t)(row0 + ai * HALF + m * 16) * ldc + col0 + bj * HALF);
; template <class Epi, class Sched, bool ALIGN_EPI = false, bool SP2 = false>
; __device__ __forceinline__ void gemm_phase(PG8_LAS unsigned char* lds, const Gemm g, const Sched& S, const Epi& E, const int wave_in) {
;     ...
;             PG8_LDA(At, 1, 1); PG8_STAGE(PG8_SB(1, 0), b3, voffB); PG8_STAGE(PG8_SB(1, 1), b3 + hstep, voffB); PG8_STAGE(PG8_SA(1, 0), a3, voffA);
;             PG8_WAIT_V(8); PG8_WAIT_L(0); PG8_BAR; PG8_MMA(1, 0, At, B0); PG8_MMA(1, 1, At, B1); PG8_BAR; PG8_SCHED;
	s_add_i32 s24, s73, s29
	v_lshl_add_u64 v[206:207], v[206:207], 0, s[50:51]
	s_mov_b32 m0, s24
	ds_read_b128 v[170:173], v193 offset:49152
	ds_read_b128 v[174:177], v193 offset:50176
	ds_read_b128 v[178:181], v193 offset:51200
	ds_read_b128 v[182:185], v193 offset:52224
	ds_read_b128 v[186:189], v193 offset:53248
	ds_read_b128 v[194:197], v193 offset:54272
	ds_read_b128 v[198:201], v193 offset:55296
	ds_read_b128 v[202:205], v193 offset:56320
	global_load_lds_dwordx4 v[206:207], off
	v_lshl_add_u64 v[206:207], v[214:215], 0, s[50:51]
	s_add_i32 m0, s24, 0x2000
	s_add_i32 s24, s74, s29
	global_load_lds_dwordx4 v[206:207], off
	v_lshl_add_u64 v[206:207], v[216:217], 0, s[50:51]
	s_mov_b32 m0, s24
	s_nop 0
	global_load_lds_dwordx4 v[206:207], off
	v_lshl_add_u64 v[206:207], v[232:233], 0, s[50:51]
	s_add_i32 m0, s24, 0x2000
	s_nop 0
	global_load_lds_dwordx4 v[206:207], off
	v_lshl_add_u64 v[206:207], v[234:235], 0, s[50:51]
	s_mov_b32 m0, s48
	s_nop 0
	global_load_lds_dwordx4 v[206:207], off
	v_lshl_add_u64 v[206:207], v[236:237], 0, s[50:51]
	s_mov_b32 m0, s49
	s_nop 0
	global_load_lds_dwordx4 v[206:207], off
	s_waitcnt vmcnt(8)
	s_waitcnt lgkmcnt(0)
	s_barrier
	s_setprio 1
	s_waitcnt lgkmcnt(0)
	v_mfma_f32_16x16x32_bf16 v[60:63], v[120:123], v[170:173], v[60:63]
	v_mfma_f32_16x16x32_bf16 v[56:59], v[136:139], v[170:173], v[56:59]
	v_mfma_f32_16x16x32_bf16 v[44:47], v[120:123], v[178:181], v[44:47]
	v_mfma_f32_16x16x32_bf16 v[40:43], v[136:139], v[178:181], v[40:43]
	v_mfma_f32_16x16x32_bf16 v[28:31], v[120:123], v[186:189], v[28:31]
	v_mfma_f32_16x16x32_bf16 v[24:27], v[136:139], v[186:189], v[24:27]
	v_mfma_f32_16x16x32_bf16 v[12:15], v[120:123], v[198:201], v[12:15]
	v_mfma_f32_16x16x32_bf16 v[8:11], v[136:139], v[198:201], v[8:11]
	v_mfma_f32_16x16x32_bf16 v[60:63], v[132:135], v[174:177], v[60:63]
	v_mfma_f32_16x16x32_bf16 v[56:59], v[140:143], v[174:177], v[56:59]
	v_mfma_f32_16x16x32_bf16 v[44:47], v[132:135], v[182:185], v[44:47]
	v_mfma_f32_16x16x32_bf16 v[40:43], v[140:143], v[182:185], v[40:43]
	v_mfma_f32_16x16x32_bf16 v[28:31], v[132:135], v[194:197], v[28:31]
	v_mfma_f32_16x16x32_bf16 v[24:27], v[140:143], v[194:197], v[24:27]
	v_mfma_f32_16x16x32_bf16 v[12:15], v[132:135], v[202:205], v[12:15]
	v_mfma_f32_16x16x32_bf16 v[8:11], v[140:143], v[202:205], v[8:11]
	s_setprio 0
	s_setprio 1
	v_mfma_f32_16x16x32_bf16 v[52:55], v[144:147], v[170:173], v[52:55]
	v_mfma_f32_16x16x32_bf16 v[48:51], v[152:155], v[170:173], v[48:51]
	v_mfma_f32_16x16x32_bf16 v[36:39], v[144:147], v[178:181], v[36:39]
	v_mfma_f32_16x16x32_bf16 v[32:35], v[152:155], v[178:181], v[32:35]
	v_mfma_f32_16x16x32_bf16 v[20:23], v[144:147], v[186:189], v[20:23]
	v_mfma_f32_16x16x32_bf16 v[16:19], v[152:155], v[186:189], v[16:19]
	v_mfma_f32_16x16x32_bf16 v[4:7], v[144:147], v[198:201], v[4:7]
	v_mfma_f32_16x16x32_bf16 v[0:3], v[152:155], v[198:201], v[0:3]
	v_mfma_f32_16x16x32_bf16 v[52:55], v[148:151], v[174:177], v[52:55]
	v_mfma_f32_16x16x32_bf16 v[48:51], v[166:169], v[174:177], v[48:51]
	v_mfma_f32_16x16x32_bf16 v[36:39], v[148:151], v[182:185], v[36:39]
	v_mfma_f32_16x16x32_bf16 v[32:35], v[166:169], v[182:185], v[32:35]
	v_mfma_f32_16x16x32_bf16 v[20:23], v[148:151], v[194:197], v[20:23]
	v_mfma_f32_16x16x32_bf16 v[16:19], v[166:169], v[194:197], v[16:19]
	v_mfma_f32_16x16x32_bf16 v[4:7], v[148:151], v[202:205], v[4:7]
	v_mfma_f32_16x16x32_bf16 v[0:3], v[166:169], v[202:205], v[0:3]
	s_setprio 0
	s_barrier
	s_add_u32 s44, s44, 0x100
	s_addc_u32 s45, s45, 0
	s_add_u32 s20, s20, 0x100
	s_addc_u32 s21, s21, 0
	s_cmp_ge_u32 s72, s37
	s_mov_b32 s24, s72
	s_cbranch_scc0 .LBB0_59
	v_readlane_b32 s20, v251, 28
	v_readlane_b32 s21, v251, 29
	v_lshl_add_u32 v250, s43, 8, v190
	v_lshl_or_b32 v249, s42, 8, v192
	v_lshlrev_b32_e32 v248, 12, v250
	v_lshl_add_u32 v238, v249, 1, v248
	v_add_u32_e32 v239, 0x10000, v238
	v_add_u32_e32 v240, 0x20000, v238
	v_add_u32_e32 v241, 0x30000, v238
	v_add_u32_e32 v242, 0x80000, v238
	v_add_u32_e32 v243, 0x90000, v238
	v_add_u32_e32 v244, 0xa0000, v238
	v_add_u32_e32 v245, 0xb0000, v238
	global_load_dwordx4 v[120:123], v238, s[20:21]
	global_load_dwordx4 v[132:135], v238, s[20:21] offset:256
	global_load_dwordx4 v[136:139], v239, s[20:21]
	global_load_dwordx4 v[140:143], v239, s[20:21] offset:256
	global_load_dwordx4 v[144:147], v240, s[20:21]
	global_load_dwordx4 v[148:151], v240, s[20:21] offset:256
	global_load_dwordx4 v[152:155], v241, s[20:21]
	global_load_dwordx4 v[166:169], v241, s[20:21] offset:256
	global_load_dwordx4 v[170:173], v242, s[20:21]
	global_load_dwordx4 v[174:177], v242, s[20:21] offset:256
	global_load_dwordx4 v[178:181], v243, s[20:21]
	global_load_dwordx4 v[182:185], v243, s[20:21] offset:256
	global_load_dwordx4 v[186:189], v244, s[20:21]
	global_load_dwordx4 v[194:197], v244, s[20:21] offset:256
	global_load_dwordx4 v[198:201], v245, s[20:21]
	global_load_dwordx4 v[202:205], v245, s[20:21] offset:256
	s_and_b64 vcc, exec, s[12:13]
	s_cbranch_vccz .LBB0_62
	s_barrier
; __device__ __forceinline__ u32x4 pack8(const f32x4 v0, const f32x4 v1) { u32x4 w; w.x = cvt_pk_bf16(v0[0], v0[1]); w.y = cvt_pk_bf16(v0[2], v0[3]); w.z = cvt_pk_bf16(v1[0], v1[1]); w.w = cvt_pk_bf16(v1[2], v1[3]); return w; }
; __device__ __forceinline__ float sq4(const f32x4 v) { return (v[0] * v[0] + v[1] * v[1]) + (v[2] * v[2] + v[3] * v[3]); }
; __device__ __forceinline__ float sum_fq(float v) { v += __shfl_xor(v, 16); v += __shfl_xor(v, 32); return v; }
;     __device__ __forceinline__ void operator()(const f32x4 (&acc)[2][2][4][2], const Unit& u, int wr, int wc, int fr, int fq) const {
;     ...
;             for (int m = 0; m < 4; ++m) {
;                 const int row = row0 + ai * HALF + m * 16; float s = 0.f;
; #pragma unroll
;                 for (int bj = 0; bj < 2; ++bj) {
;                     const size_t p = (size_t)row * ldc + col0 + bj * HALF; const u32x4 rw = res[m][bj];
;                     const f32x4 r0 = (f32x4){__builtin_bit_cast(float, rw.x << 16), __builtin_bit_cast(float, rw.x & 0xffff0000u), __builtin_bit_cast(float, rw.y << 16), __builtin_bit_cast(float, rw.y & 0xffff0000u)};
;                     const f32x4 r1 = (f32x4){__builtin_bit_cast(float, rw.z << 16), __builtin_bit_cast(float, rw.z & 0xffff0000u), __builtin_bit_cast(float, rw.w << 16), __builtin_bit_cast(float, rw.w & 0xffff0000u)};
;                     const f32x4 v0 = acc[ai][bj][m][0] + r0, v1 = acc[ai][bj][m][1] + r1;
;                     if (xout) { *(f32x4*)(xout + p) = v0; *(f32x4*)(xout + p + 4) = v1; }
;                     else { *(u32x4*)(xb + p) = pack8(v0, v1); s += sq4(v0) + sq4(v1); }
;                 }
;                 if (!xout) { s = sum_fq(s); if (fq == 0) atomicAdd(ssnext + row, s); }
.LBB0_62:
	v_readlane_b32 s76, v251, 32
	s_and_b64 vcc, exec, s[16:17]
	s_cbranch_vccnz .Lresid_xout
	s_waitcnt vmcnt(14)
	v_lshlrev_b32_e32 v246, 16, v120
	v_lshlrev_b32_e32 v247, 16, v121
	v_lshlrev_b32_e32 v248, 16, v122
	v_lshlrev_b32_e32 v249, 16, v123
	v_and_b32_e32 v120, 0xffff0000, v120
	v_and_b32_e32 v121, 0xffff0000, v121
	v_and_b32_e32 v122, 0xffff0000, v122
	v_and_b32_e32 v123, 0xffff0000, v123
	v_add_f32_e32 v128, v128, v246
	v_add_f32_e32 v129, v129, v120
	v_add_f32_e32 v130, v130, v247
	v_add_f32_e32 v131, v131, v121
	v_add_f32_e32 v124, v124, v248
	v_add_f32_e32 v125, v125, v122
	v_add_f32_e32 v126, v126, v249
	v_add_f32_e32 v127, v127, v123
	v_cvt_pk_bf16_f32 v120, v128, v129
	v_cvt_pk_bf16_f32 v121, v130, v131
	v_cvt_pk_bf16_f32 v122, v124, v125
	v_cvt_pk_bf16_f32 v123, v126, v127
	global_store_dwordx4 v238, v[120:123], s[20:21]
	v_lshlrev_b32_e32 v246, 16, v132
	v_lshlrev_b32_e32 v247, 16, v133
	v_lshlrev_b32_e32 v248, 16, v134
	v_lshlrev_b32_e32 v249, 16, v135
	v_and_b32_e32 v132, 0xffff0000, v132
	v_and_b32_e32 v133, 0xffff0000, v133
	v_and_b32_e32 v134, 0xffff0000, v134
	v_and_b32_e32 v135, 0xffff0000, v135
	v_add_f32_e32 v116, v116, v246
	v_add_f32_e32 v117, v117, v132
	v_add_f32_e32 v118, v118, v247
	v_add_f32_e32 v119, v119, v133
	v_add_f32_e32 v112, v112, v248
	v_add_f32_e32 v113, v113, v134
	v_add_f32_e32 v114, v114, v249
	v_add_f32_e32 v115, v115, v135
	v_cvt_pk_bf16_f32 v132, v116, v117
	v_cvt_pk_bf16_f32 v133, v118, v119
	v_cvt_pk_bf16_f32 v134, v112, v113
	v_cvt_pk_bf16_f32 v135, v114, v115
	global_store_dwordx4 v238, v[132:135], s[20:21] offset:256
	v_mul_f32_e32 v128, v128, v128
	v_fmac_f32_e32 v128, v129, v129
	v_fmac_f32_e32 v128, v130, v130
	v_fmac_f32_e32 v128, v131, v131
	v_fmac_f32_e32 v128, v124, v124
	v_fmac_f32_e32 v128, v125, v125
	v_fmac_f32_e32 v128, v126, v126
	v_fmac_f32_e32 v128, v127, v127
	v_fmac_f32_e32 v128, v116, v116
	v_fmac_f32_e32 v128, v117, v117
	v_fmac_f32_e32 v128, v118, v118
	v_fmac_f32_e32 v128, v119, v119
	v_fmac_f32_e32 v128, v112, v112
	v_fmac_f32_e32 v128, v113, v113
	v_fmac_f32_e32 v128, v114, v114
	v_fmac_f32_e32 v128, v115, v115
	s_waitcnt vmcnt(14)
	v_lshlrev_b32_e32 v246, 16, v136
	v_lshlrev_b32_e32 v247, 16, v137
	v_lshlrev_b32_e32 v248, 16, v138
	v_lshlrev_b32_e32 v249, 16, v139
	v_and_b32_e32 v136, 0xffff0000, v136
	v_and_b32_e32 v137, 0xffff0000, v137
	v_and_b32_e32 v138, 0xffff0000, v138
	v_and_b32_e32 v139, 0xffff0000, v139
	v_add_f32_e32 v108, v108, v246
	v_add_f32_e32 v109, v109, v136
	v_add_f32_e32 v110, v110, v247
	v_add_f32_e32 v111, v111, v137
	v_add_f32_e32 v104, v104, v248
	v_add_f32_e32 v105, v105, v138
	v_add_f32_e32 v106, v106, v249
	v_add_f32_e32 v107, v107, v139
	v_cvt_pk_bf16_f32 v136, v108, v109
	v_cvt_pk_bf16_f32 v137, v110, v111
	v_cvt_pk_bf16_f32 v138, v104, v105
	v_cvt_pk_bf16_f32 v139, v106, v107
	global_store_dwordx4 v239, v[136:139], s[20:21]
	v_lshlrev_b32_e32 v246, 16, v140
	v_lshlrev_b32_e32 v247, 16, v141
	v_lshlrev_b32_e32 v248, 16, v142
	v_lshlrev_b32_e32 v249, 16, v143
	v_and_b32_e32 v140, 0xffff0000, v140
	v_and_b32_e32 v141, 0xffff0000, v141
	v_and_b32_e32 v142, 0xffff0000, v142
	v_and_b32_e32 v143, 0xffff0000, v143
	v_add_f32_e32 v100, v100, v246
	v_add_f32_e32 v101, v101, v140
	v_add_f32_e32 v102, v102, v247
	v_add_f32_e32 v103, v103, v141
	v_add_f32_e32 v96, v96, v248
	v_add_f32_e32 v97, v97, v142
	v_add_f32_e32 v98, v98, v249
	v_add_f32_e32 v99, v99, v143
	v_cvt_pk_bf16_f32 v140, v100, v101
	v_cvt_pk_bf16_f32 v141, v102, v103
	v_cvt_pk_bf16_f32 v142, v96, v97
	v_cvt_pk_bf16_f32 v143, v98, v99
	global_store_dwordx4 v239, v[140:143], s[20:21] offset:256
	v_mul_f32_e32 v108, v108, v108
	v_fmac_f32_e32 v108, v109, v109
	v_fmac_f32_e32 v108, v110, v110
	v_fmac_f32_e32 v108, v111, v111
	v_fmac_f32_e32 v108, v104, v104
	v_fmac_f32_e32 v108, v105, v105
	v_fmac_f32_e32 v108, v106, v106
	v_fmac_f32_e32 v108, v107, v107
	v_fmac_f32_e32 v108, v100, v100
	v_fmac_f32_e32 v108, v101, v101
	v_fmac_f32_e32 v108, v102, v102
	v_fmac_f32_e32 v108, v103, v103
	v_fmac_f32_e32 v108, v96, v96
	v_fmac_f32_e32 v108, v97, v97
	v_fmac_f32_e32 v108, v98, v98
	v_fmac_f32_e32 v108, v99, v99
	s_waitcnt vmcnt(14)
	v_lshlrev_b32_e32 v246, 16, v144
	v_lshlrev_b32_e32 v247, 16, v145
	v_lshlrev_b32_e32 v248, 16, v146
	v_lshlrev_b32_e32 v249, 16, v147
	v_and_b32_e32 v144, 0xffff0000, v144
	v_and_b32_e32 v145, 0xffff0000, v145
	v_and_b32_e32 v146, 0xffff0000, v146
	v_and_b32_e32 v147, 0xffff0000, v147
	v_add_f32_e32 v92, v92, v246
	v_add_f32_e32 v93, v93, v144
	v_add_f32_e32 v94, v94, v247
	v_add_f32_e32 v95, v95, v145
	v_add_f32_e32 v88, v88, v248
	v_add_f32_e32 v89, v89, v146
	v_add_f32_e32 v90, v90, v249
	v_add_f32_e32 v91, v91, v147
	v_cvt_pk_bf16_f32 v144, v92, v93
	v_cvt_pk_bf16_f32 v145, v94, v95
	v_cvt_pk_bf16_f32 v146, v88, v89
	v_cvt_pk_bf16_f32 v147, v90, v91
	global_store_dwordx4 v240, v[144:147], s[20:21]
	v_lshlrev_b32_e32 v246, 16, v148
	v_lshlrev_b32_e32 v247, 16, v149
	v_lshlrev_b32_e32 v248, 16, v150
	v_lshlrev_b32_e32 v249, 16, v151
	v_and_b32_e32 v148, 0xffff0000, v148
	v_and_b32_e32 v149, 0xffff0000, v149
	v_and_b32_e32 v150, 0xffff0000, v150
	v_and_b32_e32 v151, 0xffff0000, v151
	v_add_f32_e32 v84, v84, v246
	v_add_f32_e32 v85, v85, v148
	v_add_f32_e32 v86, v86, v247
	v_add_f32_e32 v87, v87, v149
	v_add_f32_e32 v80, v80, v248
	v_add_f32_e32 v81, v81, v150
	v_add_f32_e32 v82, v82, v249
	v_add_f32_e32 v83, v83, v151
	v_cvt_pk_bf16_f32 v148, v84, v85
	v_cvt_pk_bf16_f32 v149, v86, v87
	v_cvt_pk_bf16_f32 v150, v80, v81
	v_cvt_pk_bf16_f32 v151, v82, v83
	global_store_dwordx4 v240, v[148:151], s[20:21] offset:256
	v_mul_f32_e32 v92, v92, v92
	v_fmac_f32_e32 v92, v93, v93
	v_fmac_f32_e32 v92, v94, v94
	v_fmac_f32_e32 v92, v95, v95
	v_fmac_f32_e32 v92, v88, v88
	v_fmac_f32_e32 v92, v89, v89
	v_fmac_f32_e32 v92, v90, v90
	v_fmac_f32_e32 v92, v91, v91
	v_fmac_f32_e32 v92, v84, v84
	v_fmac_f32_e32 v92, v85, v85
	v_fmac_f32_e32 v92, v86, v86
	v_fmac_f32_e32 v92, v87, v87
	v_fmac_f32_e32 v92, v80, v80
	v_fmac_f32_e32 v92, v81, v81
	v_fmac_f32_e32 v92, v82, v82
	v_fmac_f32_e32 v92, v83, v83
	s_waitcnt vmcnt(14)
; __device__ __forceinline__ u32x4 pack8(const f32x4 v0, const f32x4 v1) { u32x4 w; w.x = cvt_pk_bf16(v0[0], v0[1]); w.y = cvt_pk_bf16(v0[2], v0[3]); w.z = cvt_pk_bf16(v1[0], v1[1]); w.w = cvt_pk_bf16(v1[2], v1[3]); return w; }
; __device__ __forceinline__ float sq4(const f32x4 v) { return (v[0] * v[0] + v[1] * v[1]) + (v[2] * v[2] + v[3] * v[3]); }
;     __device__ __forceinline__ void operator()(const f32x4 (&acc)[2][2][4][2], const Unit& u, int wr, int wc, int fr, int fq) const {
;     ...
;             for (int m = 0; m < 4; ++m) {
;                 const int row = row0 + ai * HALF + m * 16; float s = 0.f;
; #pragma unroll
;                 for (int bj = 0; bj < 2; ++bj) {
;                     const size_t p = (size_t)row * ldc + col0 + bj * HALF; const u32x4 rw = res[m][bj];
;                     const f32x4 r0 = (f32x4){__builtin_bit_cast(float, rw.x << 16), __builtin_bit_cast(float, rw.x & 0xffff0000u), __builtin_bit_cast(float, rw.y << 16), __builtin_bit_cast(float, rw.y & 0xffff0000u)};
;                     const f32x4 r1 = (f32x4){__builtin_bit_cast(float, rw.z << 16), __builtin_bit_cast(float, rw.z & 0xffff0000u), __builtin_bit_cast(float, rw.w << 16), __builtin_bit_cast(float, rw.w & 0xffff0000u)};
;                     const f32x4 v0 = acc[ai][bj][m][0] + r0, v1 = acc[ai][bj][m][1] + r1;
;                     if (xout) { *(f32x4*)(xout + p) = v0; *(f32x4*)(xout + p + 4) = v1; }
;                     else { *(u32x4*)(xb + p) = pack8(v0, v1); s += sq4(v0) + sq4(v1); }
	v_lshlrev_b32_e32 v246, 16, v152
	v_lshlrev_b32_e32 v247, 16, v153
	v_lshlrev_b32_e32 v248, 16, v154
	v_lshlrev_b32_e32 v249, 16, v155
	v_and_b32_e32 v152, 0xffff0000, v152
	v_and_b32_e32 v153, 0xffff0000, v153
	v_and_b32_e32 v154, 0xffff0000, v154
	v_and_b32_e32 v155, 0xffff0000, v155
	v_add_f32_e32 v76, v76, v246
	v_add_f32_e32 v77, v77, v152
	v_add_f32_e32 v78, v78, v247
	v_add_f32_e32 v79, v79, v153
	v_add_f32_e32 v72, v72, v248
	v_add_f32_e32 v73, v73, v154
	v_add_f32_e32 v74, v74, v249
	v_add_f32_e32 v75, v75, v155
	v_cvt_pk_bf16_f32 v152, v76, v77
	v_cvt_pk_bf16_f32 v153, v78, v79
	v_cvt_pk_bf16_f32 v154, v72, v73
	v_cvt_pk_bf16_f32 v155, v74, v75
	global_store_dwordx4 v241, v[152:155], s[20:21]
	v_lshlrev_b32_e32 v246, 16, v166
	v_lshlrev_b32_e32 v247, 16, v167
	v_lshlrev_b32_e32 v248, 16, v168
	v_lshlrev_b32_e32 v249, 16, v169
	v_and_b32_e32 v166, 0xffff0000, v166
	v_and_b32_e32 v167, 0xffff0000, v167
	v_and_b32_e32 v168, 0xffff0000, v168
	v_and_b32_e32 v169, 0xffff0000, v169
	v_add_f32_e32 v68, v68, v246
	v_add_f32_e32 v69, v69, v166
	v_add_f32_e32 v70, v70, v247
	v_add_f32_e32 v71, v71, v167
	v_add_f32_e32 v64, v64, v248
	v_add_f32_e32 v65, v65, v168
	v_add_f32_e32 v66, v66, v249
	v_add_f32_e32 v67, v67, v169
	v_cvt_pk_bf16_f32 v166, v68, v69
	v_cvt_pk_bf16_f32 v167, v70, v71
	v_cvt_pk_bf16_f32 v168, v64, v65
	v_cvt_pk_bf16_f32 v169, v66, v67
	global_store_dwordx4 v241, v[166:169], s[20:21] offset:256
	v_mul_f32_e32 v76, v76, v76
	v_fmac_f32_e32 v76, v77, v77
	v_fmac_f32_e32 v76, v78, v78
	v_fmac_f32_e32 v76, v79, v79
	v_fmac_f32_e32 v76, v72, v72
	v_fmac_f32_e32 v76, v73, v73
	v_fmac_f32_e32 v76, v74, v74
	v_fmac_f32_e32 v76, v75, v75
	v_fmac_f32_e32 v76, v68, v68
	v_fmac_f32_e32 v76, v69, v69
	v_fmac_f32_e32 v76, v70, v70
	v_fmac_f32_e32 v76, v71, v71
	v_fmac_f32_e32 v76, v64, v64
	v_fmac_f32_e32 v76, v65, v65
	v_fmac_f32_e32 v76, v66, v66
	v_fmac_f32_e32 v76, v67, v67
	s_waitcnt vmcnt(14)
	v_lshlrev_b32_e32 v246, 16, v170
	v_lshlrev_b32_e32 v247, 16, v171
	v_lshlrev_b32_e32 v248, 16, v172
	v_lshlrev_b32_e32 v249, 16, v173
	v_and_b32_e32 v170, 0xffff0000, v170
	v_and_b32_e32 v171, 0xffff0000, v171
	v_and_b32_e32 v172, 0xffff0000, v172
	v_and_b32_e32 v173, 0xffff0000, v173
	v_add_f32_e32 v60, v60, v246
	v_add_f32_e32 v61, v61, v170
	v_add_f32_e32 v62, v62, v247
	v_add_f32_e32 v63, v63, v171
	v_add_f32_e32 v56, v56, v248
	v_add_f32_e32 v57, v57, v172
	v_add_f32_e32 v58, v58, v249
	v_add_f32_e32 v59, v59, v173
	v_cvt_pk_bf16_f32 v170, v60, v61
	v_cvt_pk_bf16_f32 v171, v62, v63
	v_cvt_pk_bf16_f32 v172, v56, v57
	v_cvt_pk_bf16_f32 v173, v58, v59
	global_store_dwordx4 v242, v[170:173], s[20:21]
	v_lshlrev_b32_e32 v246, 16, v174
	v_lshlrev_b32_e32 v247, 16, v175
	v_lshlrev_b32_e32 v248, 16, v176
	v_lshlrev_b32_e32 v249, 16, v177
	v_and_b32_e32 v174, 0xffff0000, v174
	v_and_b32_e32 v175, 0xffff0000, v175
	v_and_b32_e32 v176, 0xffff0000, v176
	v_and_b32_e32 v177, 0xffff0000, v177
	v_add_f32_e32 v52, v52, v246
	v_add_f32_e32 v53, v53, v174
	v_add_f32_e32 v54, v54, v247
	v_add_f32_e32 v55, v55, v175
	v_add_f32_e32 v48, v48, v248
	v_add_f32_e32 v49, v49, v176
	v_add_f32_e32 v50, v50, v249
	v_add_f32_e32 v51, v51, v177
	v_cvt_pk_bf16_f32 v174, v52, v53
	v_cvt_pk_bf16_f32 v175, v54, v55
	v_cvt_pk_bf16_f32 v176, v48, v49
	v_cvt_pk_bf16_f32 v177, v50, v51
	global_store_dwordx4 v242, v[174:177], s[20:21] offset:256
	v_mul_f32_e32 v60, v60, v60
	v_fmac_f32_e32 v60, v61, v61
	v_fmac_f32_e32 v60, v62, v62
	v_fmac_f32_e32 v60, v63, v63
	v_fmac_f32_e32 v60, v56, v56
	v_fmac_f32_e32 v60, v57, v57
	v_fmac_f32_e32 v60, v58, v58
	v_fmac_f32_e32 v60, v59, v59
	v_fmac_f32_e32 v60, v52, v52
	v_fmac_f32_e32 v60, v53, v53
	v_fmac_f32_e32 v60, v54, v54
	v_fmac_f32_e32 v60, v55, v55
	v_fmac_f32_e32 v60, v48, v48
	v_fmac_f32_e32 v60, v49, v49
	v_fmac_f32_e32 v60, v50, v50
	v_fmac_f32_e32 v60, v51, v51
	s_waitcnt vmcnt(14)
	v_lshlrev_b32_e32 v246, 16, v178
	v_lshlrev_b32_e32 v247, 16, v179
	v_lshlrev_b32_e32 v248, 16, v180
	v_lshlrev_b32_e32 v249, 16, v181
	v_and_b32_e32 v178, 0xffff0000, v178
	v_and_b32_e32 v179, 0xffff0000, v179
	v_and_b32_e32 v180, 0xffff0000, v180
	v_and_b32_e32 v181, 0xffff0000, v181
	v_add_f32_e32 v44, v44, v246
	v_add_f32_e32 v45, v45, v178
	v_add_f32_e32 v46, v46, v247
	v_add_f32_e32 v47, v47, v179
	v_add_f32_e32 v40, v40, v248
	v_add_f32_e32 v41, v41, v180
	v_add_f32_e32 v42, v42, v249
	v_add_f32_e32 v43, v43, v181
	v_cvt_pk_bf16_f32 v178, v44, v45
	v_cvt_pk_bf16_f32 v179, v46, v47
	v_cvt_pk_bf16_f32 v180, v40, v41
	v_cvt_pk_bf16_f32 v181, v42, v43
	global_store_dwordx4 v243, v[178:181], s[20:21]
	v_lshlrev_b32_e32 v246, 16, v182
	v_lshlrev_b32_e32 v247, 16, v183
	v_lshlrev_b32_e32 v248, 16, v184
	v_lshlrev_b32_e32 v249, 16, v185
	v_and_b32_e32 v182, 0xffff0000, v182
	v_and_b32_e32 v183, 0xffff0000, v183
	v_and_b32_e32 v184, 0xffff0000, v184
	v_and_b32_e32 v185, 0xffff0000, v185
	v_add_f32_e32 v36, v36, v246
	v_add_f32_e32 v37, v37, v182
	v_add_f32_e32 v38, v38, v247
	v_add_f32_e32 v39, v39, v183
	v_add_f32_e32 v32, v32, v248
	v_add_f32_e32 v33, v33, v184
	v_add_f32_e32 v34, v34, v249
	v_add_f32_e32 v35, v35, v185
	v_cvt_pk_bf16_f32 v182, v36, v37
	v_cvt_pk_bf16_f32 v183, v38, v39
	v_cvt_pk_bf16_f32 v184, v32, v33
	v_cvt_pk_bf16_f32 v185, v34, v35
	global_store_dwordx4 v243, v[182:185], s[20:21] offset:256
	v_mul_f32_e32 v44, v44, v44
	v_fmac_f32_e32 v44, v45, v45
	v_fmac_f32_e32 v44, v46, v46
	v_fmac_f32_e32 v44, v47, v47
	v_fmac_f32_e32 v44, v40, v40
	v_fmac_f32_e32 v44, v41, v41
	v_fmac_f32_e32 v44, v42, v42
	v_fmac_f32_e32 v44, v43, v43
	v_fmac_f32_e32 v44, v36, v36
	v_fmac_f32_e32 v44, v37, v37
	v_fmac_f32_e32 v44, v38, v38
	v_fmac_f32_e32 v44, v39, v39
	v_fmac_f32_e32 v44, v32, v32
	v_fmac_f32_e32 v44, v33, v33
	v_fmac_f32_e32 v44, v34, v34
	v_fmac_f32_e32 v44, v35, v35
	s_waitcnt vmcnt(14)
; __device__ __forceinline__ u32x4 pack8(const f32x4 v0, const f32x4 v1) { u32x4 w; w.x = cvt_pk_bf16(v0[0], v0[1]); w.y = cvt_pk_bf16(v0[2], v0[3]); w.z = cvt_pk_bf16(v1[0], v1[1]); w.w = cvt_pk_bf16(v1[2], v1[3]); return w; }
; __device__ __forceinline__ float sq4(const f32x4 v) { return (v[0] * v[0] + v[1] * v[1]) + (v[2] * v[2] + v[3] * v[3]); }
; __device__ __forceinline__ float sum_fq(float v) { v += __shfl_xor(v, 16); v += __shfl_xor(v, 32); return v; }
;     __device__ __forceinline__ void operator()(const f32x4 (&acc)[2][2][4][2], const Unit& u, int wr, int wc, int fr, int fq) const {
;     ...
;             for (int m = 0; m < 4; ++m) {
;                 const int row = row0 + ai * HALF + m * 16; float s = 0.f;
; #pragma unroll
;                 for (int bj = 0; bj < 2; ++bj) {
;                     const size_t p = (size_t)row * ldc + col0 + bj * HALF; const u32x4 rw = res[m][bj];
;                     const f32x4 r0 = (f32x4){__builtin_bit_cast(float, rw.x << 16), __builtin_bit_cast(float, rw.x & 0xffff0000u), __builtin_bit_cast(float, rw.y << 16), __builtin_bit_cast(float, rw.y & 0xffff0000u)};
;                     const f32x4 r1 = (f32x4){__builtin_bit_cast(float, rw.z << 16), __builtin_bit_cast(float, rw.z & 0xffff0000u), __builtin_bit_cast(float, rw.w << 16), __builtin_bit_cast(float, rw.w & 0xffff0000u)};
;                     const f32x4 v0 = acc[ai][bj][m][0] + r0, v1 = acc[ai][bj][m][1] + r1;
;                     if (xout) { *(f32x4*)(xout + p) = v0; *(f32x4*)(xout + p + 4) = v1; }
;                     else { *(u32x4*)(xb + p) = pack8(v0, v1); s += sq4(v0) + sq4(v1); }
;                 }
;                 if (!xout) { s = sum_fq(s); if (fq == 0) atomicAdd(ssnext + row, s); }
	v_lshlrev_b32_e32 v246, 16, v186
	v_lshlrev_b32_e32 v247, 16, v187
	v_lshlrev_b32_e32 v248, 16, v188
	v_lshlrev_b32_e32 v249, 16, v189
	v_and_b32_e32 v186, 0xffff0000, v186
	v_and_b32_e32 v187, 0xffff0000, v187
	v_and_b32_e32 v188, 0xffff0000, v188
	v_and_b32_e32 v189, 0xffff0000, v189
	v_add_f32_e32 v28, v28, v246
	v_add_f32_e32 v29, v29, v186
	v_add_f32_e32 v30, v30, v247
	v_add_f32_e32 v31, v31, v187
	v_add_f32_e32 v24, v24, v248
	v_add_f32_e32 v25, v25, v188
	v_add_f32_e32 v26, v26, v249
	v_add_f32_e32 v27, v27, v189
	v_cvt_pk_bf16_f32 v186, v28, v29
	v_cvt_pk_bf16_f32 v187, v30, v31
	v_cvt_pk_bf16_f32 v188, v24, v25
	v_cvt_pk_bf16_f32 v189, v26, v27
	global_store_dwordx4 v244, v[186:189], s[20:21]
	v_lshlrev_b32_e32 v246, 16, v194
	v_lshlrev_b32_e32 v247, 16, v195
	v_lshlrev_b32_e32 v248, 16, v196
	v_lshlrev_b32_e32 v249, 16, v197
	v_and_b32_e32 v194, 0xffff0000, v194
	v_and_b32_e32 v195, 0xffff0000, v195
	v_and_b32_e32 v196, 0xffff0000, v196
	v_and_b32_e32 v197, 0xffff0000, v197
	v_add_f32_e32 v20, v20, v246
	v_add_f32_e32 v21, v21, v194
	v_add_f32_e32 v22, v22, v247
	v_add_f32_e32 v23, v23, v195
	v_add_f32_e32 v16, v16, v248
	v_add_f32_e32 v17, v17, v196
	v_add_f32_e32 v18, v18, v249
	v_add_f32_e32 v19, v19, v197
	v_cvt_pk_bf16_f32 v194, v20, v21
	v_cvt_pk_bf16_f32 v195, v22, v23
	v_cvt_pk_bf16_f32 v196, v16, v17
	v_cvt_pk_bf16_f32 v197, v18, v19
	global_store_dwordx4 v244, v[194:197], s[20:21] offset:256
	v_mul_f32_e32 v28, v28, v28
	v_fmac_f32_e32 v28, v29, v29
	v_fmac_f32_e32 v28, v30, v30
	v_fmac_f32_e32 v28, v31, v31
	v_fmac_f32_e32 v28, v24, v24
	v_fmac_f32_e32 v28, v25, v25
	v_fmac_f32_e32 v28, v26, v26
	v_fmac_f32_e32 v28, v27, v27
	v_fmac_f32_e32 v28, v20, v20
	v_fmac_f32_e32 v28, v21, v21
	v_fmac_f32_e32 v28, v22, v22
	v_fmac_f32_e32 v28, v23, v23
	v_fmac_f32_e32 v28, v16, v16
	v_fmac_f32_e32 v28, v17, v17
	v_fmac_f32_e32 v28, v18, v18
	v_fmac_f32_e32 v28, v19, v19
	s_waitcnt vmcnt(14)
	v_lshlrev_b32_e32 v246, 16, v198
	v_lshlrev_b32_e32 v247, 16, v199
	v_lshlrev_b32_e32 v248, 16, v200
	v_lshlrev_b32_e32 v249, 16, v201
	v_and_b32_e32 v198, 0xffff0000, v198
	v_and_b32_e32 v199, 0xffff0000, v199
	v_and_b32_e32 v200, 0xffff0000, v200
	v_and_b32_e32 v201, 0xffff0000, v201
	v_add_f32_e32 v12, v12, v246
	v_add_f32_e32 v13, v13, v198
	v_add_f32_e32 v14, v14, v247
	v_add_f32_e32 v15, v15, v199
	v_add_f32_e32 v8, v8, v248
	v_add_f32_e32 v9, v9, v200
	v_add_f32_e32 v10, v10, v249
	v_add_f32_e32 v11, v11, v201
	v_cvt_pk_bf16_f32 v198, v12, v13
	v_cvt_pk_bf16_f32 v199, v14, v15
	v_cvt_pk_bf16_f32 v200, v8, v9
	v_cvt_pk_bf16_f32 v201, v10, v11
	global_store_dwordx4 v245, v[198:201], s[20:21]
	v_lshlrev_b32_e32 v246, 16, v202
	v_lshlrev_b32_e32 v247, 16, v203
	v_lshlrev_b32_e32 v248, 16, v204
	v_lshlrev_b32_e32 v249, 16, v205
	v_and_b32_e32 v202, 0xffff0000, v202
	v_and_b32_e32 v203, 0xffff0000, v203
	v_and_b32_e32 v204, 0xffff0000, v204
	v_and_b32_e32 v205, 0xffff0000, v205
	v_add_f32_e32 v4, v4, v246
	v_add_f32_e32 v5, v5, v202
	v_add_f32_e32 v6, v6, v247
	v_add_f32_e32 v7, v7, v203
	v_add_f32_e32 v0, v0, v248
	v_add_f32_e32 v1, v1, v204
	v_add_f32_e32 v2, v2, v249
	v_add_f32_e32 v3, v3, v205
	v_cvt_pk_bf16_f32 v202, v4, v5
	v_cvt_pk_bf16_f32 v203, v6, v7
	v_cvt_pk_bf16_f32 v204, v0, v1
	v_cvt_pk_bf16_f32 v205, v2, v3
	global_store_dwordx4 v245, v[202:205], s[20:21] offset:256
	v_mul_f32_e32 v12, v12, v12
	v_fmac_f32_e32 v12, v13, v13
	v_fmac_f32_e32 v12, v14, v14
	v_fmac_f32_e32 v12, v15, v15
	v_fmac_f32_e32 v12, v8, v8
	v_fmac_f32_e32 v12, v9, v9
	v_fmac_f32_e32 v12, v10, v10
	v_fmac_f32_e32 v12, v11, v11
	v_fmac_f32_e32 v12, v4, v4
	v_fmac_f32_e32 v12, v5, v5
	v_fmac_f32_e32 v12, v6, v6
	v_fmac_f32_e32 v12, v7, v7
	v_fmac_f32_e32 v12, v0, v0
	v_fmac_f32_e32 v12, v1, v1
	v_fmac_f32_e32 v12, v2, v2
	v_fmac_f32_e32 v12, v3, v3
	v_xor_b32_e32 v246, 16, v220
	v_xor_b32_e32 v247, 32, v220
	v_lshlrev_b32_e32 v246, 2, v246
	v_lshlrev_b32_e32 v247, 2, v247
	s_nop 1
	ds_bpermute_b32 v120, v246, v128
	ds_bpermute_b32 v121, v246, v108
	ds_bpermute_b32 v122, v246, v92
	ds_bpermute_b32 v123, v246, v76
	ds_bpermute_b32 v132, v246, v60
	ds_bpermute_b32 v133, v246, v44
	ds_bpermute_b32 v134, v246, v28
	ds_bpermute_b32 v135, v246, v12
	s_waitcnt lgkmcnt(0)
	v_add_f32_e32 v128, v128, v120
	v_add_f32_e32 v108, v108, v121
	v_add_f32_e32 v92, v92, v122
	v_add_f32_e32 v76, v76, v123
	v_add_f32_e32 v60, v60, v132
	v_add_f32_e32 v44, v44, v133
	v_add_f32_e32 v28, v28, v134
	v_add_f32_e32 v12, v12, v135
	ds_bpermute_b32 v120, v247, v128
	ds_bpermute_b32 v121, v247, v108
	ds_bpermute_b32 v122, v247, v92
	ds_bpermute_b32 v123, v247, v76
	ds_bpermute_b32 v132, v247, v60
	ds_bpermute_b32 v133, v247, v44
	ds_bpermute_b32 v134, v247, v28
	ds_bpermute_b32 v135, v247, v12
	s_waitcnt lgkmcnt(0)
	v_add_f32_e32 v128, v128, v120
	v_add_f32_e32 v108, v108, v121
	v_add_f32_e32 v92, v92, v122
	v_add_f32_e32 v76, v76, v123
	v_add_f32_e32 v60, v60, v132
	v_add_f32_e32 v44, v44, v133
	v_add_f32_e32 v28, v28, v134
	v_add_f32_e32 v12, v12, v135
	v_lshlrev_b32_e32 v248, 2, v250
	s_and_saveexec_b64 s[20:21], s[38:39]
	global_atomic_add_f32 v248, v128, s[6:7]
	global_atomic_add_f32 v248, v108, s[6:7] offset:64
	global_atomic_add_f32 v248, v92, s[6:7] offset:128
	global_atomic_add_f32 v248, v76, s[6:7] offset:192
	global_atomic_add_f32 v248, v60, s[6:7] offset:512
	global_atomic_add_f32 v248, v44, s[6:7] offset:576
	global_atomic_add_f32 v248, v28, s[6:7] offset:640
	global_atomic_add_f32 v248, v12, s[6:7] offset:704
	s_or_b64 exec, exec, s[20:21]
	s_branch .LBB0_158
;     __device__ __forceinline__ void operator()(const f32x4 (&acc)[2][2][4][2], const Unit& u, int wr, int wc, int fr, int fq) const {
;     ...
;             for (int m = 0; m < 4; ++m) {
;                 const int row = row0 + ai * HALF + m * 16; float s = 0.f;
; #pragma unroll
;                 for (int bj = 0; bj < 2; ++bj) {
;                     const size_t p = (size_t)row * ldc + col0 + bj * HALF; const u32x4 rw = res[m][bj];
;                     const f32x4 r0 = (f32x4){__builtin_bit_cast(float, rw.x << 16), __builtin_bit_cast(float, rw.x & 0xffff0000u), __builtin_bit_cast(float, rw.y << 16), __builtin_bit_cast(float, rw.y & 0xffff0000u)};
;                     const f32x4 r1 = (f32x4){__builtin_bit_cast(float, rw.z << 16), __builtin_bit_cast(float, rw.z & 0xffff0000u), __builtin_bit_cast(float, rw.w << 16), __builtin_bit_cast(float, rw.w & 0xffff0000u)};
;                     const f32x4 v0 = acc[ai][bj][m][0] + r0, v1 = acc[ai][bj][m][1] + r1;
;                     if (xout) { *(f32x4*)(xout + p) = v0; *(f32x4*)(xout + p + 4) = v1; }
.Lresid_xout:
	s_waitcnt vmcnt(14)
	v_lshlrev_b32_e32 v238, 1, v238
	v_lshlrev_b32_e32 v246, 16, v120
	v_lshlrev_b32_e32 v247, 16, v121
	v_lshlrev_b32_e32 v248, 16, v122
	v_lshlrev_b32_e32 v249, 16, v123
	v_and_b32_e32 v120, 0xffff0000, v120
	v_and_b32_e32 v121, 0xffff0000, v121
	v_and_b32_e32 v122, 0xffff0000, v122
	v_and_b32_e32 v123, 0xffff0000, v123
	v_add_f32_e32 v128, v128, v246
	v_add_f32_e32 v129, v129, v120
	v_add_f32_e32 v130, v130, v247
	v_add_f32_e32 v131, v131, v121
	v_add_f32_e32 v124, v124, v248
	v_add_f32_e32 v125, v125, v122
	v_add_f32_e32 v126, v126, v249
	v_add_f32_e32 v127, v127, v123
	global_store_dwordx4 v238, v[128:131], s[22:23]
	global_store_dwordx4 v238, v[124:127], s[22:23] offset:16
	v_lshlrev_b32_e32 v246, 16, v132
	v_lshlrev_b32_e32 v247, 16, v133
	v_lshlrev_b32_e32 v248, 16, v134
	v_lshlrev_b32_e32 v249, 16, v135
	v_and_b32_e32 v132, 0xffff0000, v132
	v_and_b32_e32 v133, 0xffff0000, v133
	v_and_b32_e32 v134, 0xffff0000, v134
	v_and_b32_e32 v135, 0xffff0000, v135
	v_add_f32_e32 v116, v116, v246
	v_add_f32_e32 v117, v117, v132
	v_add_f32_e32 v118, v118, v247
	v_add_f32_e32 v119, v119, v133
	v_add_f32_e32 v112, v112, v248
	v_add_f32_e32 v113, v113, v134
	v_add_f32_e32 v114, v114, v249
	v_add_f32_e32 v115, v115, v135
	global_store_dwordx4 v238, v[116:119], s[22:23] offset:512
	global_store_dwordx4 v238, v[112:115], s[22:23] offset:528
	s_waitcnt vmcnt(16)
	v_lshlrev_b32_e32 v239, 1, v239
	v_lshlrev_b32_e32 v246, 16, v136
	v_lshlrev_b32_e32 v247, 16, v137
	v_lshlrev_b32_e32 v248, 16, v138
	v_lshlrev_b32_e32 v249, 16, v139
	v_and_b32_e32 v136, 0xffff0000, v136
	v_and_b32_e32 v137, 0xffff0000, v137
	v_and_b32_e32 v138, 0xffff0000, v138
	v_and_b32_e32 v139, 0xffff0000, v139
	v_add_f32_e32 v108, v108, v246
	v_add_f32_e32 v109, v109, v136
	v_add_f32_e32 v110, v110, v247
	v_add_f32_e32 v111, v111, v137
	v_add_f32_e32 v104, v104, v248
	v_add_f32_e32 v105, v105, v138
	v_add_f32_e32 v106, v106, v249
	v_add_f32_e32 v107, v107, v139
	global_store_dwordx4 v239, v[108:111], s[22:23]
	global_store_dwordx4 v239, v[104:107], s[22:23] offset:16
	v_lshlrev_b32_e32 v246, 16, v140
	v_lshlrev_b32_e32 v247, 16, v141
	v_lshlrev_b32_e32 v248, 16, v142
	v_lshlrev_b32_e32 v249, 16, v143
	v_and_b32_e32 v140, 0xffff0000, v140
	v_and_b32_e32 v141, 0xffff0000, v141
	v_and_b32_e32 v142, 0xffff0000, v142
	v_and_b32_e32 v143, 0xffff0000, v143
	v_add_f32_e32 v100, v100, v246
	v_add_f32_e32 v101, v101, v140
	v_add_f32_e32 v102, v102, v247
	v_add_f32_e32 v103, v103, v141
	v_add_f32_e32 v96, v96, v248
	v_add_f32_e32 v97, v97, v142
	v_add_f32_e32 v98, v98, v249
	v_add_f32_e32 v99, v99, v143
	global_store_dwordx4 v239, v[100:103], s[22:23] offset:512
	global_store_dwordx4 v239, v[96:99], s[22:23] offset:528
	s_waitcnt vmcnt(18)
	v_lshlrev_b32_e32 v240, 1, v240
	v_lshlrev_b32_e32 v246, 16, v144
	v_lshlrev_b32_e32 v247, 16, v145
	v_lshlrev_b32_e32 v248, 16, v146
	v_lshlrev_b32_e32 v249, 16, v147
	v_and_b32_e32 v144, 0xffff0000, v144
	v_and_b32_e32 v145, 0xffff0000, v145
	v_and_b32_e32 v146, 0xffff0000, v146
	v_and_b32_e32 v147, 0xffff0000, v147
	v_add_f32_e32 v92, v92, v246
	v_add_f32_e32 v93, v93, v144
	v_add_f32_e32 v94, v94, v247
	v_add_f32_e32 v95, v95, v145
	v_add_f32_e32 v88, v88, v248
	v_add_f32_e32 v89, v89, v146
	v_add_f32_e32 v90, v90, v249
	v_add_f32_e32 v91, v91, v147
	global_store_dwordx4 v240, v[92:95], s[22:23]
	global_store_dwordx4 v240, v[88:91], s[22:23] offset:16
	v_lshlrev_b32_e32 v246, 16, v148
	v_lshlrev_b32_e32 v247, 16, v149
	v_lshlrev_b32_e32 v248, 16, v150
	v_lshlrev_b32_e32 v249, 16, v151
	v_and_b32_e32 v148, 0xffff0000, v148
	v_and_b32_e32 v149, 0xffff0000, v149
	v_and_b32_e32 v150, 0xffff0000, v150
	v_and_b32_e32 v151, 0xffff0000, v151
	v_add_f32_e32 v84, v84, v246
	v_add_f32_e32 v85, v85, v148
	v_add_f32_e32 v86, v86, v247
	v_add_f32_e32 v87, v87, v149
	v_add_f32_e32 v80, v80, v248
	v_add_f32_e32 v81, v81, v150
	v_add_f32_e32 v82, v82, v249
	v_add_f32_e32 v83, v83, v151
	global_store_dwordx4 v240, v[84:87], s[22:23] offset:512
	global_store_dwordx4 v240, v[80:83], s[22:23] offset:528
	s_waitcnt vmcnt(20)
	v_lshlrev_b32_e32 v241, 1, v241
	v_lshlrev_b32_e32 v246, 16, v152
	v_lshlrev_b32_e32 v247, 16, v153
	v_lshlrev_b32_e32 v248, 16, v154
	v_lshlrev_b32_e32 v249, 16, v155
	v_and_b32_e32 v152, 0xffff0000, v152
	v_and_b32_e32 v153, 0xffff0000, v153
	v_and_b32_e32 v154, 0xffff0000, v154
	v_and_b32_e32 v155, 0xffff0000, v155
	v_add_f32_e32 v76, v76, v246
	v_add_f32_e32 v77, v77, v152
	v_add_f32_e32 v78, v78, v247
	v_add_f32_e32 v79, v79, v153
	v_add_f32_e32 v72, v72, v248
	v_add_f32_e32 v73, v73, v154
	v_add_f32_e32 v74, v74, v249
	v_add_f32_e32 v75, v75, v155
	global_store_dwordx4 v241, v[76:79], s[22:23]
	global_store_dwordx4 v241, v[72:75], s[22:23] offset:16
	v_lshlrev_b32_e32 v246, 16, v166
	v_lshlrev_b32_e32 v247, 16, v167
	v_lshlrev_b32_e32 v248, 16, v168
	v_lshlrev_b32_e32 v249, 16, v169
	v_and_b32_e32 v166, 0xffff0000, v166
	v_and_b32_e32 v167, 0xffff0000, v167
	v_and_b32_e32 v168, 0xffff0000, v168
	v_and_b32_e32 v169, 0xffff0000, v169
	v_add_f32_e32 v68, v68, v246
	v_add_f32_e32 v69, v69, v166
	v_add_f32_e32 v70, v70, v247
	v_add_f32_e32 v71, v71, v167
	v_add_f32_e32 v64, v64, v248
	v_add_f32_e32 v65, v65, v168
	v_add_f32_e32 v66, v66, v249
	v_add_f32_e32 v67, v67, v169
	global_store_dwordx4 v241, v[68:71], s[22:23] offset:512
	global_store_dwordx4 v241, v[64:67], s[22:23] offset:528
	s_waitcnt vmcnt(22)
;     __device__ __forceinline__ void operator()(const f32x4 (&acc)[2][2][4][2], const Unit& u, int wr, int wc, int fr, int fq) const {
;     ...
;             for (int m = 0; m < 4; ++m) {
;                 const int row = row0 + ai * HALF + m * 16; float s = 0.f;
; #pragma unroll
;                 for (int bj = 0; bj < 2; ++bj) {
;                     const size_t p = (size_t)row * ldc + col0 + bj * HALF; const u32x4 rw = res[m][bj];
;                     const f32x4 r0 = (f32x4){__builtin_bit_cast(float, rw.x << 16), __builtin_bit_cast(float, rw.x & 0xffff0000u), __builtin_bit_cast(float, rw.y << 16), __builtin_bit_cast(float, rw.y & 0xffff0000u)};
;                     const f32x4 r1 = (f32x4){__builtin_bit_cast(float, rw.z << 16), __builtin_bit_cast(float, rw.z & 0xffff0000u), __builtin_bit_cast(float, rw.w << 16), __builtin_bit_cast(float, rw.w & 0xffff0000u)};
;                     const f32x4 v0 = acc[ai][bj][m][0] + r0, v1 = acc[ai][bj][m][1] + r1;
;                     if (xout) { *(f32x4*)(xout + p) = v0; *(f32x4*)(xout + p + 4) = v1; }
	v_lshlrev_b32_e32 v242, 1, v242
	v_lshlrev_b32_e32 v246, 16, v170
	v_lshlrev_b32_e32 v247, 16, v171
	v_lshlrev_b32_e32 v248, 16, v172
	v_lshlrev_b32_e32 v249, 16, v173
	v_and_b32_e32 v170, 0xffff0000, v170
	v_and_b32_e32 v171, 0xffff0000, v171
	v_and_b32_e32 v172, 0xffff0000, v172
	v_and_b32_e32 v173, 0xffff0000, v173
	v_add_f32_e32 v60, v60, v246
	v_add_f32_e32 v61, v61, v170
	v_add_f32_e32 v62, v62, v247
	v_add_f32_e32 v63, v63, v171
	v_add_f32_e32 v56, v56, v248
	v_add_f32_e32 v57, v57, v172
	v_add_f32_e32 v58, v58, v249
	v_add_f32_e32 v59, v59, v173
	global_store_dwordx4 v242, v[60:63], s[22:23]
	global_store_dwordx4 v242, v[56:59], s[22:23] offset:16
	v_lshlrev_b32_e32 v246, 16, v174
	v_lshlrev_b32_e32 v247, 16, v175
	v_lshlrev_b32_e32 v248, 16, v176
	v_lshlrev_b32_e32 v249, 16, v177
	v_and_b32_e32 v174, 0xffff0000, v174
	v_and_b32_e32 v175, 0xffff0000, v175
	v_and_b32_e32 v176, 0xffff0000, v176
	v_and_b32_e32 v177, 0xffff0000, v177
	v_add_f32_e32 v52, v52, v246
	v_add_f32_e32 v53, v53, v174
	v_add_f32_e32 v54, v54, v247
	v_add_f32_e32 v55, v55, v175
	v_add_f32_e32 v48, v48, v248
	v_add_f32_e32 v49, v49, v176
	v_add_f32_e32 v50, v50, v249
	v_add_f32_e32 v51, v51, v177
	global_store_dwordx4 v242, v[52:55], s[22:23] offset:512
	global_store_dwordx4 v242, v[48:51], s[22:23] offset:528
	s_waitcnt vmcnt(24)
	v_lshlrev_b32_e32 v243, 1, v243
	v_lshlrev_b32_e32 v246, 16, v178
	v_lshlrev_b32_e32 v247, 16, v179
	v_lshlrev_b32_e32 v248, 16, v180
	v_lshlrev_b32_e32 v249, 16, v181
	v_and_b32_e32 v178, 0xffff0000, v178
	v_and_b32_e32 v179, 0xffff0000, v179
	v_and_b32_e32 v180, 0xffff0000, v180
	v_and_b32_e32 v181, 0xffff0000, v181
	v_add_f32_e32 v44, v44, v246
	v_add_f32_e32 v45, v45, v178
	v_add_f32_e32 v46, v46, v247
	v_add_f32_e32 v47, v47, v179
	v_add_f32_e32 v40, v40, v248
	v_add_f32_e32 v41, v41, v180
	v_add_f32_e32 v42, v42, v249
	v_add_f32_e32 v43, v43, v181
	global_store_dwordx4 v243, v[44:47], s[22:23]
	global_store_dwordx4 v243, v[40:43], s[22:23] offset:16
	v_lshlrev_b32_e32 v246, 16, v182
	v_lshlrev_b32_e32 v247, 16, v183
	v_lshlrev_b32_e32 v248, 16, v184
	v_lshlrev_b32_e32 v249, 16, v185
	v_and_b32_e32 v182, 0xffff0000, v182
	v_and_b32_e32 v183, 0xffff0000, v183
	v_and_b32_e32 v184, 0xffff0000, v184
	v_and_b32_e32 v185, 0xffff0000, v185
	v_add_f32_e32 v36, v36, v246
	v_add_f32_e32 v37, v37, v182
	v_add_f32_e32 v38, v38, v247
	v_add_f32_e32 v39, v39, v183
	v_add_f32_e32 v32, v32, v248
	v_add_f32_e32 v33, v33, v184
	v_add_f32_e32 v34, v34, v249
	v_add_f32_e32 v35, v35, v185
	global_store_dwordx4 v243, v[36:39], s[22:23] offset:512
	global_store_dwordx4 v243, v[32:35], s[22:23] offset:528
	s_waitcnt vmcnt(26)
	v_lshlrev_b32_e32 v244, 1, v244
	v_lshlrev_b32_e32 v246, 16, v186
	v_lshlrev_b32_e32 v247, 16, v187
	v_lshlrev_b32_e32 v248, 16, v188
	v_lshlrev_b32_e32 v249, 16, v189
	v_and_b32_e32 v186, 0xffff0000, v186
	v_and_b32_e32 v187, 0xffff0000, v187
	v_and_b32_e32 v188, 0xffff0000, v188
	v_and_b32_e32 v189, 0xffff0000, v189
	v_add_f32_e32 v28, v28, v246
	v_add_f32_e32 v29, v29, v186
	v_add_f32_e32 v30, v30, v247
	v_add_f32_e32 v31, v31, v187
	v_add_f32_e32 v24, v24, v248
	v_add_f32_e32 v25, v25, v188
	v_add_f32_e32 v26, v26, v249
	v_add_f32_e32 v27, v27, v189
	global_store_dwordx4 v244, v[28:31], s[22:23]
	global_store_dwordx4 v244, v[24:27], s[22:23] offset:16
	v_lshlrev_b32_e32 v246, 16, v194
	v_lshlrev_b32_e32 v247, 16, v195
	v_lshlrev_b32_e32 v248, 16, v196
	v_lshlrev_b32_e32 v249, 16, v197
	v_and_b32_e32 v194, 0xffff0000, v194
	v_and_b32_e32 v195, 0xffff0000, v195
	v_and_b32_e32 v196, 0xffff0000, v196
	v_and_b32_e32 v197, 0xffff0000, v197
	v_add_f32_e32 v20, v20, v246
	v_add_f32_e32 v21, v21, v194
	v_add_f32_e32 v22, v22, v247
	v_add_f32_e32 v23, v23, v195
	v_add_f32_e32 v16, v16, v248
	v_add_f32_e32 v17, v17, v196
	v_add_f32_e32 v18, v18, v249
	v_add_f32_e32 v19, v19, v197
	global_store_dwordx4 v244, v[20:23], s[22:23] offset:512
	global_store_dwordx4 v244, v[16:19], s[22:23] offset:528
	s_waitcnt vmcnt(28)
	v_lshlrev_b32_e32 v245, 1, v245
	v_lshlrev_b32_e32 v246, 16, v198
	v_lshlrev_b32_e32 v247, 16, v199
	v_lshlrev_b32_e32 v248, 16, v200
	v_lshlrev_b32_e32 v249, 16, v201
	v_and_b32_e32 v198, 0xffff0000, v198
	v_and_b32_e32 v199, 0xffff0000, v199
	v_and_b32_e32 v200, 0xffff0000, v200
	v_and_b32_e32 v201, 0xffff0000, v201
	v_add_f32_e32 v12, v12, v246
	v_add_f32_e32 v13, v13, v198
	v_add_f32_e32 v14, v14, v247
	v_add_f32_e32 v15, v15, v199
	v_add_f32_e32 v8, v8, v248
	v_add_f32_e32 v9, v9, v200
	v_add_f32_e32 v10, v10, v249
	v_add_f32_e32 v11, v11, v201
	global_store_dwordx4 v245, v[12:15], s[22:23]
	global_store_dwordx4 v245, v[8:11], s[22:23] offset:16
	v_lshlrev_b32_e32 v246, 16, v202
	v_lshlrev_b32_e32 v247, 16, v203
	v_lshlrev_b32_e32 v248, 16, v204
	v_lshlrev_b32_e32 v249, 16, v205
	v_and_b32_e32 v202, 0xffff0000, v202
	v_and_b32_e32 v203, 0xffff0000, v203
	v_and_b32_e32 v204, 0xffff0000, v204
	v_and_b32_e32 v205, 0xffff0000, v205
	v_add_f32_e32 v4, v4, v246
	v_add_f32_e32 v5, v5, v202
	v_add_f32_e32 v6, v6, v247
	v_add_f32_e32 v7, v7, v203
	v_add_f32_e32 v0, v0, v248
	v_add_f32_e32 v1, v1, v204
	v_add_f32_e32 v2, v2, v249
	v_add_f32_e32 v3, v3, v205
	global_store_dwordx4 v245, v[4:7], s[22:23] offset:512
	global_store_dwordx4 v245, v[0:3], s[22:23] offset:528
